# full stack: v32 plus alignment-barrier move plus RG-LRU gate-to-scan barrier removed
# speedup vs baseline: 1.0094x; 1.0050x over previous
; #define LAS __attribute__((address_space(3)))
; __device__ __forceinline__ float fsigmoid(float x) { return __builtin_amdgcn_rcpf(1.0f + __builtin_amdgcn_exp2f(-1.4426950408889634f * x)); }
; __device__ __forceinline__ void rglru_unit(LAS unsigned char* lds, int unit, const bf16* PBp, bf16* MGp, float* SSQRp, const float* cw, const float* cbias, const float* wa, const float* ba, const float* wx, const float* bxp, const float* lam) {
;     ...
;         {
;             typedef float f32x4m __attribute__((ext_vector_type(4)));
;             const rg_bf16x8 a0 = *(const LAS rg_bf16x8*)(XRB + (wave * 16 + fr) * 72 + 8 * fq), a1 = *(const LAS rg_bf16x8*)(XRB + (wave * 16 + fr) * 72 + 32 + 8 * fq);
;             f32x4m d[4];
; #pragma unroll
;             for (int nb = 0; nb < 4; ++nb) { d[nb] = (f32x4m){0.f, 0.f, 0.f, 0.f};
;                 d[nb] = __builtin_amdgcn_mfma_f32_16x16x32_bf16(a0, wb[nb][0], d[nb], 0, 0, 0); d[nb] = __builtin_amdgcn_mfma_f32_16x16x32_bf16(a1, wb[nb][1], d[nb], 0, 0, 0); }
; #pragma unroll
;             for (int cb = 0; cb < 2; ++cb)
; #pragma unroll
;                 for (int e = 0; e < 4; ++e) {
;                     const int tok = wave * 16 + 4 * fq + e, cl = 16 * cb + fr;
;                     const float r = fsigmoid(d[cb][e] + gba[cb]), ig = fsigmoid(d[2 + cb][e] + gbx[cb]);
;                     const float a = __builtin_amdgcn_exp2f(r * gsp[cb]);
;                     const float om = fmaxf(1.0f - a * a, 0.0f);
;                     AL[tok * 32 + cl] = a; UL[tok * 32 + cl] = __builtin_amdgcn_sqrtf(om) * (ig * XRF[tok * 32 + cl]);
;                 }
;         }
;         __syncthreads();
;         float av[8], uv[8];
; #pragma unroll
;         for (int k = 0; k < 8; ++k) { av[k] = AL[(ss * 8 + k) * 32 + sc]; uv[k] = UL[(ss * 8 + k) * 32 + sc]; }
;         { float h = 0.f, p = 1.f;
; #pragma unroll
;           for (int k = 0; k < 8; ++k) { h = av[k] * h + uv[k]; p *= av[k]; }
;           PE[(ss * 32 + sc) * 2] = p; PE[(ss * 32 + sc) * 2 + 1] = h; }
.LBB0_452:
	s_waitcnt lgkmcnt(0)
	s_barrier
	ds_read_b128 v[72:75], v134
	ds_read_b128 v[76:79], v134 offset:64
	v_add_u32_e32 v1, 0x4800, v138
	ds_read2_b32 v[92:93], v1 offset1:32
	ds_read2_b32 v[94:95], v1 offset0:64 offset1:96
	ds_read2_b32 v[96:97], v1 offset0:16 offset1:48
	ds_read2_b32 v[98:99], v1 offset0:80 offset1:112
	v_mov_b32_e32 v2, 0xbfb8aa3b
	v_mov_b32_e32 v120, 1.0
	v_mov_b32_e32 v112, v123
	v_mov_b32_e32 v114, v125
	v_mov_b32_e32 v116, v127
	s_waitcnt lgkmcnt(4)
	v_mfma_f32_16x16x32_bf16 v[80:83], v[72:75], v[20:23], 0
	v_mfma_f32_16x16x32_bf16 v[84:87], v[72:75], v[52:55], 0
	v_mfma_f32_16x16x32_bf16 v[80:83], v[76:79], v[32:35], v[80:83]
	v_mfma_f32_16x16x32_bf16 v[84:87], v[76:79], v[56:59], v[84:87]
	v_mfma_f32_16x16x32_bf16 v[88:91], v[72:75], v[36:39], 0
	v_mfma_f32_16x16x32_bf16 v[108:111], v[72:75], v[60:63], 0
	v_mfma_f32_16x16x32_bf16 v[88:91], v[76:79], v[48:51], v[88:91]
	v_mfma_f32_16x16x32_bf16 v[108:111], v[76:79], v[64:67], v[108:111]
	v_add_u32_e32 v3, 0x8800, v138
	v_add_u32_e32 v121, 0xc800, v138
	s_nop 3
	s_waitcnt lgkmcnt(0)
	v_pk_add_f32 v[80:81], v[80:81], v[122:123] op_sel_hi:[1,0]
	v_pk_add_f32 v[84:85], v[84:85], v[112:113] op_sel_hi:[1,0]
	v_pk_mul_f32 v[80:81], v[80:81], v[2:3] op_sel_hi:[1,0]
	v_pk_mul_f32 v[84:85], v[84:85], v[2:3] op_sel_hi:[1,0]
	v_exp_f32_e32 v80, v80
	v_exp_f32_e32 v81, v81
	v_exp_f32_e32 v84, v84
	v_exp_f32_e32 v85, v85
	v_pk_add_f32 v[80:81], v[80:81], v[120:121] op_sel_hi:[1,0]
	v_pk_add_f32 v[84:85], v[84:85], v[120:121] op_sel_hi:[1,0]
	v_rcp_f32_e32 v80, v80
	v_rcp_f32_e32 v81, v81
	v_rcp_f32_e32 v84, v84
	v_rcp_f32_e32 v85, v85
	v_pk_mul_f32 v[118:119], v[80:81], v[128:129] op_sel_hi:[1,0]
	v_pk_mul_f32 v[78:79], v[92:93], v[84:85]
	v_exp_f32_e32 v118, v118
	v_exp_f32_e32 v119, v119
	s_nop 0
	v_fma_f32 v76, -v118, v118, 1.0
	v_fma_f32 v77, -v119, v119, 1.0
	v_max_f32_e32 v76, 0, v76
	v_max_f32_e32 v77, 0, v77
	v_sqrt_f32_e32 v76, v76
	v_sqrt_f32_e32 v77, v77
	ds_write2_b32 v3, v118, v119 offset0:0 offset1:32
	v_pk_mul_f32 v[78:79], v[78:79], v[76:77]
	ds_write2_b32 v121, v78, v79 offset0:0 offset1:32
	v_pk_add_f32 v[82:83], v[82:83], v[122:123] op_sel_hi:[1,0]
	v_pk_add_f32 v[86:87], v[86:87], v[112:113] op_sel_hi:[1,0]
	v_pk_mul_f32 v[82:83], v[82:83], v[2:3] op_sel_hi:[1,0]
	v_pk_mul_f32 v[86:87], v[86:87], v[2:3] op_sel_hi:[1,0]
	v_exp_f32_e32 v82, v82
	v_exp_f32_e32 v83, v83
	v_exp_f32_e32 v86, v86
	v_exp_f32_e32 v87, v87
	v_pk_add_f32 v[82:83], v[82:83], v[120:121] op_sel_hi:[1,0]
	v_pk_add_f32 v[86:87], v[86:87], v[120:121] op_sel_hi:[1,0]
	v_rcp_f32_e32 v82, v82
	v_rcp_f32_e32 v83, v83
	v_rcp_f32_e32 v86, v86
	v_rcp_f32_e32 v87, v87
	v_pk_mul_f32 v[118:119], v[82:83], v[128:129] op_sel_hi:[1,0]
	v_pk_mul_f32 v[78:79], v[94:95], v[86:87]
	v_exp_f32_e32 v118, v118
	v_exp_f32_e32 v119, v119
	s_nop 0
	v_fma_f32 v76, -v118, v118, 1.0
	v_fma_f32 v77, -v119, v119, 1.0
	v_max_f32_e32 v76, 0, v76
	v_max_f32_e32 v77, 0, v77
	v_sqrt_f32_e32 v76, v76
	v_sqrt_f32_e32 v77, v77
	ds_write2_b32 v3, v118, v119 offset0:64 offset1:96
	v_pk_mul_f32 v[78:79], v[78:79], v[76:77]
	ds_write2_b32 v121, v78, v79 offset0:64 offset1:96
	v_pk_add_f32 v[88:89], v[88:89], v[124:125] op_sel_hi:[1,0]
	v_pk_add_f32 v[108:109], v[108:109], v[114:115] op_sel_hi:[1,0]
	v_pk_mul_f32 v[88:89], v[88:89], v[2:3] op_sel_hi:[1,0]
	v_pk_mul_f32 v[108:109], v[108:109], v[2:3] op_sel_hi:[1,0]
	v_exp_f32_e32 v88, v88
	v_exp_f32_e32 v89, v89
	v_exp_f32_e32 v108, v108
	v_exp_f32_e32 v109, v109
	v_pk_add_f32 v[88:89], v[88:89], v[120:121] op_sel_hi:[1,0]
	v_pk_add_f32 v[108:109], v[108:109], v[120:121] op_sel_hi:[1,0]
	v_rcp_f32_e32 v88, v88
	v_rcp_f32_e32 v89, v89
	v_rcp_f32_e32 v108, v108
	v_rcp_f32_e32 v109, v109
	v_pk_mul_f32 v[118:119], v[88:89], v[116:117] op_sel_hi:[1,0]
	v_pk_mul_f32 v[78:79], v[96:97], v[108:109]
	v_exp_f32_e32 v118, v118
	v_exp_f32_e32 v119, v119
	s_nop 0
	v_fma_f32 v76, -v118, v118, 1.0
	v_fma_f32 v77, -v119, v119, 1.0
	v_max_f32_e32 v76, 0, v76
	v_max_f32_e32 v77, 0, v77
	v_sqrt_f32_e32 v76, v76
	v_sqrt_f32_e32 v77, v77
	ds_write2_b32 v3, v118, v119 offset0:16 offset1:48
	v_pk_mul_f32 v[78:79], v[78:79], v[76:77]
	ds_write2_b32 v121, v78, v79 offset0:16 offset1:48
	v_pk_add_f32 v[90:91], v[90:91], v[124:125] op_sel_hi:[1,0]
	v_pk_add_f32 v[110:111], v[110:111], v[114:115] op_sel_hi:[1,0]
	v_pk_mul_f32 v[90:91], v[90:91], v[2:3] op_sel_hi:[1,0]
	v_pk_mul_f32 v[110:111], v[110:111], v[2:3] op_sel_hi:[1,0]
	v_exp_f32_e32 v90, v90
	v_exp_f32_e32 v91, v91
	v_exp_f32_e32 v110, v110
	v_exp_f32_e32 v111, v111
	v_pk_add_f32 v[90:91], v[90:91], v[120:121] op_sel_hi:[1,0]
	v_pk_add_f32 v[110:111], v[110:111], v[120:121] op_sel_hi:[1,0]
	v_rcp_f32_e32 v90, v90
	v_rcp_f32_e32 v91, v91
	v_rcp_f32_e32 v110, v110
	v_rcp_f32_e32 v111, v111
	v_pk_mul_f32 v[118:119], v[90:91], v[116:117] op_sel_hi:[1,0]
	v_pk_mul_f32 v[78:79], v[98:99], v[110:111]
	v_exp_f32_e32 v118, v118
	v_exp_f32_e32 v119, v119
	s_nop 0
	v_fma_f32 v76, -v118, v118, 1.0
	v_fma_f32 v77, -v119, v119, 1.0
	v_max_f32_e32 v76, 0, v76
	v_max_f32_e32 v77, 0, v77
	v_sqrt_f32_e32 v76, v76
	v_sqrt_f32_e32 v77, v77
	ds_write2_b32 v3, v118, v119 offset0:80 offset1:112
	v_pk_mul_f32 v[78:79], v[78:79], v[76:77]
	ds_write2_b32 v121, v78, v79 offset0:80 offset1:112
	v_add_u32_e32 v1, 0x8800, v140
	s_waitcnt lgkmcnt(0)
	ds_read2_b32 v[120:121], v1 offset1:32
	v_add_u32_e32 v2, 0xc800, v140
	ds_read2_b32 v[118:119], v2 offset1:32
	ds_read2_b32 v[116:117], v1 offset0:64 offset1:96
	ds_read2_b32 v[114:115], v2 offset0:64 offset1:96
	ds_read2_b32 v[112:113], v1 offset0:128 offset1:160
	ds_read2_b32 v[110:111], v2 offset0:128 offset1:160
	ds_read2_b32 v[108:109], v1 offset0:192 offset1:224
	ds_read2_b32 v[2:3], v2 offset0:192 offset1:224
	s_waitcnt lgkmcnt(5)
	v_mov_b32_e32 v74, v116
	s_waitcnt lgkmcnt(3)
	v_mov_b32_e32 v75, v113
	v_fma_f32 v1, 0, v120, v118
	v_fma_f32 v1, v1, v121, v119
	v_fma_f32 v1, v1, v116, v114
	v_fma_f32 v1, v1, v117, v115
	v_mul_f32_e32 v72, v120, v121
	s_waitcnt lgkmcnt(2)
	v_fma_f32 v73, v1, v112, v110
	v_mov_b32_e32 v76, v117
	v_mov_b32_e32 v77, v111
	v_mul_f32_e32 v1, v72, v116
	v_pk_fma_f32 v[72:73], v[72:73], v[74:75], v[76:77]
	v_mul_f32_e32 v78, v1, v117
	v_mov_b32_e32 v79, v73
	v_mov_b32_e32 v72, v112
	s_waitcnt lgkmcnt(1)
	v_mov_b32_e32 v73, v108
	v_pk_mul_f32 v[74:75], v[78:79], v[72:73]
	v_mov_b32_e32 v76, v113
	v_mov_b32_e32 v80, v113
	s_waitcnt lgkmcnt(0)
	v_mov_b32_e32 v81, v2
	v_pk_mul_f32 v[74:75], v[74:75], v[76:77]
	v_pk_fma_f32 v[72:73], v[78:79], v[72:73], v[80:81]
	v_mov_b32_e32 v76, v109
	v_mov_b32_e32 v72, v74
	v_pk_mul_f32 v[74:75], v[74:75], v[108:109]
	v_mov_b32_e32 v78, v109
	v_mov_b32_e32 v79, v3
	v_pk_mul_f32 v[74:75], v[74:75], v[76:77]
	v_pk_fma_f32 v[72:73], v[72:73], v[108:109], v[78:79]
	s_nop 0
	v_mov_b32_e32 v75, v73
	v_add_u32_e32 v72, s89, v136
	ds_write_b64 v143, v[74:75]
	s_waitcnt lgkmcnt(0)
	s_barrier
; #define LAS __attribute__((address_space(3)))
; __device__ __forceinline__ void rglru_unit(LAS unsigned char* lds, int unit, const bf16* PBp, bf16* MGp, float* SSQRp, const float* cw, const float* cbias, const float* wa, const float* ba, const float* wx, const float* bxp, const float* lam) {
;     ...
;         float h = HIN[sc];
;         { typedef float f32x2v __attribute__((ext_vector_type(2))); f32x2v pe[15];
; #pragma unroll
;           for (int s2 = 0; s2 < 15; ++s2) pe[s2] = *(const LAS f32x2v*)(PE + (s2 * 32 + sc) * 2);
; #pragma unroll
;           for (int s2 = 0; s2 < 15; ++s2) h = (s2 < ss) ? fmaf(pe[s2].x, h, pe[s2].y) : h; }
	ds_read_b32 v1, v135
	ds_read2_b64 v[96:99], v72 offset0:32 offset1:64
	ds_read2_b64 v[92:95], v72 offset0:96 offset1:128
	ds_read2_b64 v[88:91], v72 offset0:160 offset1:192
	v_add_u32_e32 v73, 0x400, v72
	v_add_u32_e32 v72, 0x800, v72
	ds_read2_b64 v[84:87], v73 offset0:96 offset1:128
	ds_read2_b64 v[80:83], v72 offset0:32 offset1:64
	ds_read2_b64 v[76:79], v72 offset0:96 offset1:128
	ds_read2_b64 v[72:75], v72 offset0:160 offset1:192
	s_and_saveexec_b64 s[2:3], s[8:9]
	s_cbranch_execz .LBB0_454
	v_add_u32_e32 v154, 0, v136
	v_add_u32_e32 v154, 0x10800, v154
	ds_read_b64 v[154:155], v154
	s_waitcnt lgkmcnt(0)
	v_fmac_f32_e32 v155, v154, v1
	v_mov_b32_e32 v1, v155
